# GEMM tile prologues: row sum-of-squares partials loaded together (one latency) instead of a dependent load chain
# speedup vs baseline: 1.0047x; 1.0047x over previous
; __device__ __forceinline__ bool gemm_ticket(unsigned* ctr, int nt, int& tm, int& tn, char* smem) {
;     ...
;     const int j = sT[0];
;     if (j >= 32 * nt) return false;
;     const int full = nt >> 3, rem = nt & 7;
;     int tn_g, tm_g, q;
;     if (j < full * 256) { tn_g = j >> 8; const int r = j & 255; tm_g = r >> 6; q = r & 63; }
;     else { const int r = j - full * 256; tn_g = full; tm_g = r / (8 * rem); q = r % (8 * rem); }
;     tm = ((tm_g * 8 + (q & 7)) * 8) + xcd; tn = tn_g * 8 + (q >> 3); return true;
; template <class Epi>
; __device__ __forceinline__ void gemm_tile64(const bf16_t* A, const bf16_t* Bt, int tm, int tn, const Epi& epi, char* smem, const float* ssq, int nparts) {
;     ...
;     if (nparts > 0 && tid < 128) {
;         float sq = 0.f;
;         for (int q = 0; q < nparts; ++q) sq += ssq[(size_t)q * T + (size_t)tm * 128 + tid];
;         sRs[tid] = rsqrtf(sq * (1.0f / 1024.0f) + EPS);
;     }
.LBB0_47:
	s_or_b64 exec, exec, s[22:23]
	s_waitcnt lgkmcnt(0)
	s_barrier
	ds_read_b32 v0, v113 offset:33280
	s_movk_i32 s14, 0x1ff
	s_mov_b64 s[22:23], -1
	s_waitcnt lgkmcnt(0)
	v_cmp_lt_i32_e32 vcc, s14, v0
	v_readfirstlane_b32 s13, v0
	s_cbranch_vccnz .LBB0_42
	s_lshl_b32 s15, s13, 3
	s_and_b32 s14, s13, 0xc0
	s_and_b32 s15, s15, 56
	s_or_b32 s14, s14, s15
	s_or_b32 s12, s14, s12
	v_mov_b32_e32 v0, v126
	s_movk_i32 s14, 0x80
	s_nop 0
	v_cmp_gt_i32_e32 vcc, s14, v0
	s_and_saveexec_b64 s[22:23], vcc
	s_cbranch_execz .LBB0_50
	v_readlane_b32 s36, v165, 42
	v_readlane_b32 s50, v165, 56
	v_readlane_b32 s51, v165, 57
	v_readlane_b32 s37, v165, 43
	v_readlane_b32 s38, v165, 44
	v_readlane_b32 s39, v165, 45
	v_readlane_b32 s40, v165, 46
	v_readlane_b32 s41, v165, 47
	v_readlane_b32 s42, v165, 48
	v_readlane_b32 s43, v165, 49
	v_readlane_b32 s44, v165, 50
	v_readlane_b32 s45, v165, 51
	v_readlane_b32 s46, v165, 52
	v_readlane_b32 s47, v165, 53
	v_readlane_b32 s48, v165, 54
	v_readlane_b32 s49, v165, 55
	s_lshl_b32 s14, s12, 9
	s_add_u32 s14, s50, s14
	s_addc_u32 s15, s51, 0
	v_lshlrev_b32_e32 v2, 2, v0
	global_load_dword v141, v2, s[14:15]
	v_add_u32_e32 v3, 0x20000, v2
	global_load_dword v142, v3, s[14:15]
	v_add_u32_e32 v3, 0x40000, v2
	global_load_dword v143, v3, s[14:15]
	v_add_u32_e32 v3, 0x60000, v2
	global_load_dword v156, v3, s[14:15]
	v_add_u32_e32 v3, 0x80000, v2
	global_load_dword v157, v3, s[14:15]
	v_add_u32_e32 v3, 0xa0000, v2
	global_load_dword v158, v3, s[14:15]
	v_add_u32_e32 v3, 0xc0000, v2
	global_load_dword v159, v3, s[14:15]
	v_add_u32_e32 v3, 0xe0000, v2
	global_load_dword v160, v3, s[14:15]
	v_add_u32_e32 v3, 0x100000, v2
	global_load_dword v161, v3, s[14:15]
	v_add_u32_e32 v3, 0x120000, v2
	global_load_dword v162, v3, s[14:15]
	v_add_u32_e32 v3, 0x140000, v2
	global_load_dword v163, v3, s[14:15]
	v_add_u32_e32 v3, 0x160000, v2
	global_load_dword v164, v3, s[14:15]
	v_add_u32_e32 v3, 0x180000, v2
	global_load_dword v114, v3, s[14:15]
	v_add_u32_e32 v3, 0x1a0000, v2
	global_load_dword v124, v3, s[14:15]
	v_add_u32_e32 v3, 0x1c0000, v2
	global_load_dword v131, v3, s[14:15]
	v_add_u32_e32 v3, 0x1e0000, v2
	global_load_dword v135, v3, s[14:15]
	s_waitcnt vmcnt(15)
	v_add_f32_e32 v1, 0, v141
	s_waitcnt vmcnt(14)
	v_add_f32_e32 v1, v1, v142
	s_waitcnt vmcnt(13)
	v_add_f32_e32 v1, v1, v143
	s_waitcnt vmcnt(12)
	v_add_f32_e32 v1, v1, v156
	s_waitcnt vmcnt(11)
	v_add_f32_e32 v1, v1, v157
	s_waitcnt vmcnt(10)
	v_add_f32_e32 v1, v1, v158
	s_waitcnt vmcnt(9)
	v_add_f32_e32 v1, v1, v159
	s_waitcnt vmcnt(8)
	v_add_f32_e32 v1, v1, v160
	s_waitcnt vmcnt(7)
	v_add_f32_e32 v1, v1, v161
	s_waitcnt vmcnt(6)
	v_add_f32_e32 v1, v1, v162
	s_waitcnt vmcnt(5)
	v_add_f32_e32 v1, v1, v163
	s_waitcnt vmcnt(4)
	v_add_f32_e32 v1, v1, v164
	s_waitcnt vmcnt(3)
	v_add_f32_e32 v1, v1, v114
	s_waitcnt vmcnt(2)
	v_add_f32_e32 v1, v1, v124
	s_waitcnt vmcnt(1)
	v_add_f32_e32 v1, v1, v131
	s_waitcnt vmcnt(0)
	v_add_f32_e32 v1, v1, v135
	v_mov_b32_e32 v2, 0x358637bd
	v_fmamk_f32 v1, v1, 0x3a800000, v2
	v_cmp_gt_f32_e32 vcc, s7, v1
	v_mul_f32_e32 v2, 0x4b800000, v1
	s_nop 0
	v_cndmask_b32_e32 v1, v1, v2, vcc
	v_rsq_f32_e32 v1, v1
	s_nop 0
	v_mul_f32_e32 v2, 0x45800000, v1
	v_cndmask_b32_e32 v1, v1, v2, vcc
	v_lshlrev_b32_e32 v2, 2, v0
	ds_write_b32 v2, v1 offset:32768

; template <class Epi>
; __device__ __forceinline__ void gemm_tile64(const bf16_t* A, const bf16_t* Bt, int tm, int tn, const Epi& epi, char* smem, const float* ssq, int nparts) {
;     ...
;     if (nparts > 0 && tid < 128) {
;         float sq = 0.f;
;         for (int q = 0; q < nparts; ++q) sq += ssq[(size_t)q * T + (size_t)tm * 128 + tid];
;         sRs[tid] = rsqrtf(sq * (1.0f / 1024.0f) + EPS);
;     }
.LBB0_373:
	global_load_dword v141, v[2:3], off
	s_cmp_lt_u32 s12, 2
	s_cbranch_scc1 .Lssq_i_ld
	v_lshl_add_u64 v[2:3], v[2:3], 0, s[66:67]
	global_load_dword v142, v[2:3], off
	v_lshl_add_u64 v[2:3], v[2:3], 0, s[66:67]
	global_load_dword v143, v[2:3], off
	v_lshl_add_u64 v[2:3], v[2:3], 0, s[66:67]
	global_load_dword v156, v[2:3], off
	v_lshl_add_u64 v[2:3], v[2:3], 0, s[66:67]
	global_load_dword v157, v[2:3], off
	v_lshl_add_u64 v[2:3], v[2:3], 0, s[66:67]
	global_load_dword v158, v[2:3], off
	v_lshl_add_u64 v[2:3], v[2:3], 0, s[66:67]
	global_load_dword v159, v[2:3], off
	v_lshl_add_u64 v[2:3], v[2:3], 0, s[66:67]
	global_load_dword v160, v[2:3], off
.Lssq_i_ld:
	s_waitcnt vmcnt(0)
	v_add_f32_e32 v1, v1, v141
	s_cmp_lt_u32 s12, 2
	s_cbranch_scc1 .Lssq_i_sum
	v_add_f32_e32 v1, v1, v142
	v_add_f32_e32 v1, v1, v143
	v_add_f32_e32 v1, v1, v156
	v_add_f32_e32 v1, v1, v157
	v_add_f32_e32 v1, v1, v158
	v_add_f32_e32 v1, v1, v159
	v_add_f32_e32 v1, v1, v160
.Lssq_i_sum:
	s_mov_b32 s12, 0
	v_mov_b32_e32 v2, 0x358637bd
	v_fmamk_f32 v1, v1, 0x3a800000, v2
	v_mul_f32_e32 v2, 0x4b800000, v1
	v_cmp_gt_f32_e32 vcc, s7, v1
	s_nop 1
	v_cndmask_b32_e32 v1, v1, v2, vcc
	v_rsq_f32_e32 v1, v1
	s_nop 0
	v_mul_f32_e32 v2, 0x45800000, v1
	v_cndmask_b32_e32 v1, v1, v2, vcc
	v_lshlrev_b32_e32 v2, 2, v0
	ds_write_b32 v2, v1 offset:32768
